# combined + vectorised FoX decay-bound search
# baseline (speedup 1.0000x reference)
.LBB0_456:
	s_ashr_i32 s15, s2, 6
	s_and_b32 s76, s15, 7
	s_sub_i32 s77, 7, s76
	s_bitcmp1_b32 s15, 3
	s_cselect_b32 s76, s77, s76
	s_andn2_b32 s15, s15, 7
	s_or_b32 s15, s15, s76
	s_sub_i32 s11, 63, s15
	s_lshl_b32 s6, s11, 7
	s_and_b32 s3, s2, 63
	v_add_u32_e32 v116, s6, v135
	s_lshl_b32 s12, s3, 13
	v_ashrrev_i32_e32 v117, 31, v116
	v_lshl_add_u64 v[2:3], s[12:13], 0, v[116:117]
	v_lshlrev_b64 v[2:3], 7, v[2:3]
	s_lshl_b32 s7, s3, 15
	v_lshl_add_u64 v[2:3], v[110:111], 0, v[2:3]
	s_add_u32 s16, s60, s7
	s_mov_b32 s7, s13
	global_load_dwordx4 v[66:69], v[2:3], off
	global_load_dwordx4 v[70:73], v[2:3], off offset:32
	global_load_dwordx4 v[74:77], v[2:3], off offset:64
	global_load_dwordx4 v[78:81], v[2:3], off offset:96
	s_addc_u32 s17, s61, 0
	s_lshl_b64 s[18:19], s[6:7], 2
	v_lshl_add_u64 v[2:3], v[116:117], 2, s[16:17]
	s_add_u32 s18, s16, s18
	s_addc_u32 s19, s17, s19
	global_load_dword v34, v[2:3], off
	s_nop 0
	global_load_dword v2, v103, s[18:19]
	s_lshl_b32 s20, s11, 1
	s_or_b32 s22, s20, 1
	s_lshl_b32 s7, s15, 7
	s_sub_i32 s12, 0x1fbf, s7
	s_mov_b32 s11, s22
	v_mbcnt_lo_u32_b32 v3, -1, 0
	v_mbcnt_hi_u32_b32 v3, -1, v3
	s_add_i32 s23, s22, -1
	v_sub_u32_e32 v4, s23, v3
	v_subrev_u32_e32 v6, 64, v4
	v_cmp_le_i32_e64 s[80:81], 0, v4
	v_cmp_le_i32_e64 s[82:83], 0, v6
	v_max_i32_e32 v5, 0, v4
	v_max_i32_e32 v7, 0, v6
	v_lshlrev_b32_e32 v5, 8, v5
	v_lshlrev_b32_e32 v7, 8, v7
	global_load_dword v5, v5, s[16:17] offset:252
	global_load_dword v7, v7, s[16:17] offset:252
	s_waitcnt vmcnt(0)
	v_sub_f32_e32 v5, v2, v5
	v_sub_f32_e32 v7, v2, v7
	v_cmp_lt_f32_e64 s[76:77], v5, -v134
	v_cmp_lt_f32_e64 s[78:79], v7, -v134
	s_and_b64 s[76:77], s[76:77], s[80:81]
	s_and_b64 s[78:79], s[78:79], s[82:83]
	s_mov_b32 s21, 0
	s_cmp_lg_u64 s[78:79], 0
	s_cbranch_scc0 .Ljm_a
	s_ff1_i32_b64 s21, s[78:79]
	s_sub_i32 s21, s22, s21
	s_sub_i32 s21, s21, 64
